# phase 14 loop software-pipelined: next iteration's 32 loads issued at the top of the current one (v136-245 free in the last phase), waits collapsed to one counted wait
# baseline (speedup 1.0000x reference)
.LBB0_1338:
	s_cmp_lt_i32 s74, 15
	s_cselect_b64 s[2:3], -1, 0
	s_and_b64 s[0:1], s[2:3], s[0:1]
	s_cmpk_lt_i32 s64, 0x2000
	s_cselect_b64 s[2:3], -1, 0
	s_and_b64 s[0:1], s[0:1], s[2:3]
	s_andn2_b64 vcc, exec, s[0:1]
	s_movk_i32 s15, 0x2000
	s_cbranch_vccnz .LBB0_1341
	s_lshl_b32 s2, s64, 2
	s_ashr_i32 s3, s2, 31
	s_lshl_b32 s4, s33, 5
	s_lshl_b64 s[0:1], s[2:3], 12
	s_add_u32 s0, s70, s0
	v_lshlrev_b32_e32 v32, 4, v181
	v_mov_b32_e32 v33, 0
	s_addc_u32 s1, s71, s1
	s_waitcnt vmcnt(0)
	v_lshl_add_u64 v[36:37], s[0:1], 0, v[32:33]
	s_lshl_b64 s[0:1], s[2:3], 11
	s_ashr_i32 s5, s4, 31
	v_lshl_or_b32 v38, v181, 3, s0
	s_mov_b32 s0, 0x358637bd
	v_lshl_add_u64 v[34:35], s[68:69], 0, v[32:33]
	global_load_dwordx4 v[120:123], v[34:35], off
	global_load_dwordx4 v[124:127], v[34:35], off offset:1024
	global_load_dwordx4 v[128:131], v[34:35], off offset:2048
	global_load_dwordx4 v[132:135], v[34:35], off offset:3072
	s_lshl_b64 s[6:7], s[4:5], 12
	v_mov_b32_e32 v39, s1
	s_lshl_b64 s[8:9], s[4:5], 11
	s_lshl_b64 s[10:11], s[2:3], 6
	s_lshl_b64 s[12:13], s[4:5], 6
	v_mov_b32_e32 v32, 0x2680000
	s_mov_b32 s14, 0x3a800000
	v_mov_b64_e32 v[40:41], s[0:1]
	s_mov_b32 s3, 0x800000
	s_mov_b32 s5, 0x13d01000
	s_movk_i32 s18, 0x1000
	s_movk_i32 s19, 0x3000
	s_waitcnt vmcnt(0)
	s_waitcnt lgkmcnt(0)
	v_lshl_add_u64 v[136:137], s[72:73], 0, v[38:39]
	s_add_u32 s16, s72, s10
	v_add_co_u32_e64 v146, s[0:1], s5, v136
	s_addc_u32 s17, s73, s11
	s_nop 0
	v_addc_co_u32_e64 v147, s[0:1], 0, v137, s[0:1]
	s_add_u32 s0, s16, 0x2680000
	v_add_co_u32_e32 v144, vcc, 0x13d00000, v136
	s_addc_u32 s1, s17, 0
	s_nop 1
	v_addc_co_u32_e32 v145, vcc, 0, v137, vcc
	global_load_dwordx4 v[198:201], v32, s[16:17]
	global_load_dwordx4 v[202:205], v32, s[16:17] offset:64
	global_load_dwordx2 v[192:193], v[146:147], off
	global_load_dwordx2 v[190:191], v[146:147], off offset:512
	global_load_dwordx2 v[188:189], v[146:147], off offset:1024
	global_load_dwordx2 v[186:187], v[146:147], off offset:1536
	global_load_dwordx2 v[184:185], v[146:147], off offset:2048
	global_load_dwordx2 v[182:183], v[146:147], off offset:2560
	global_load_dwordx2 v[180:181], v[146:147], off offset:3072
	global_load_dwordx2 v[178:179], v[146:147], off offset:3584
	global_load_dwordx4 v[140:143], v32, s[16:17] offset:128
	global_load_dwordx4 v[136:139], v32, s[16:17] offset:192
	global_load_dwordx4 v[206:209], v33, s[0:1] offset:48
	global_load_dwordx4 v[210:213], v33, s[0:1] offset:16
	global_load_dwordx4 v[214:217], v33, s[0:1] offset:32
	s_add_u32 s0, s16, 0x2680040
	s_addc_u32 s1, s17, 0
	global_load_dwordx4 v[218:221], v33, s[0:1] offset:16
	global_load_dwordx4 v[222:225], v33, s[0:1] offset:48
	global_load_dwordx4 v[226:229], v33, s[0:1] offset:32
	global_load_dwordx2 v[230:231], v[144:145], off
	global_load_dwordx2 v[232:233], v[144:145], off offset:512
	global_load_dwordx2 v[234:235], v[144:145], off offset:1024
	global_load_dwordx2 v[236:237], v[144:145], off offset:1536
	global_load_dwordx2 v[238:239], v[144:145], off offset:2048
	global_load_dwordx2 v[240:241], v[144:145], off offset:2560
	global_load_dwordx2 v[242:243], v[144:145], off offset:3072
	global_load_dwordx2 v[244:245], v[144:145], off offset:3584
	s_add_u32 s0, s16, 0x2680080
	s_addc_u32 s1, s17, 0
	global_load_dwordx4 v[156:159], v33, s[0:1] offset:48
	global_load_dwordx4 v[164:167], v33, s[0:1] offset:16
	global_load_dwordx4 v[160:163], v33, s[0:1] offset:32
	s_add_u32 s0, s16, 0x26800c0
	s_addc_u32 s1, s17, 0
	global_load_dwordx4 v[152:155], v33, s[0:1] offset:16
	global_load_dwordx4 v[144:147], v33, s[0:1] offset:48
	global_load_dwordx4 v[148:151], v33, s[0:1] offset:32
	s_add_i32 s2, s2, s4
	s_add_u32 s10, s10, s12
	s_addc_u32 s11, s11, s13
	v_lshl_add_u64 v[38:39], v[38:39], 0, s[8:9]
	s_cmp_lt_i32 s2, 0x8000
	s_cselect_b32 s98, 1, 0
	s_waitcnt vmcnt(0)
.LBB0_1340:
	s_waitcnt vmcnt(16)
	v_mov_b64_e32 v[0:1], v[136:137]
	v_mov_b64_e32 v[2:3], v[138:139]
	v_mov_b64_e32 v[4:5], v[140:141]
	v_mov_b64_e32 v[6:7], v[142:143]
	v_mov_b64_e32 v[8:9], v[144:145]
	v_mov_b64_e32 v[10:11], v[146:147]
	v_mov_b64_e32 v[12:13], v[148:149]
	v_mov_b64_e32 v[14:15], v[150:151]
	v_mov_b64_e32 v[16:17], v[152:153]
	v_mov_b64_e32 v[18:19], v[154:155]
	v_mov_b64_e32 v[20:21], v[156:157]
	v_mov_b64_e32 v[22:23], v[158:159]
	v_mov_b64_e32 v[24:25], v[160:161]
	v_mov_b64_e32 v[26:27], v[162:163]
	v_mov_b64_e32 v[28:29], v[164:165]
	v_mov_b64_e32 v[30:31], v[166:167]
	v_mov_b64_e32 v[42:43], v[178:179]
	v_mov_b64_e32 v[44:45], v[180:181]
	v_mov_b64_e32 v[46:47], v[182:183]
	v_mov_b64_e32 v[48:49], v[184:185]
	v_mov_b64_e32 v[50:51], v[186:187]
	v_mov_b64_e32 v[52:53], v[188:189]
	v_mov_b64_e32 v[54:55], v[190:191]
	v_mov_b64_e32 v[56:57], v[192:193]
	v_mov_b64_e32 v[62:63], v[198:199]
	v_mov_b64_e32 v[64:65], v[200:201]
	v_mov_b64_e32 v[66:67], v[202:203]
	v_mov_b64_e32 v[68:69], v[204:205]
	v_mov_b64_e32 v[70:71], v[206:207]
	v_mov_b64_e32 v[72:73], v[208:209]
	v_mov_b64_e32 v[74:75], v[210:211]
	v_mov_b64_e32 v[76:77], v[212:213]
	v_mov_b64_e32 v[78:79], v[214:215]
	v_mov_b64_e32 v[80:81], v[216:217]
	v_mov_b64_e32 v[82:83], v[218:219]
	v_mov_b64_e32 v[84:85], v[220:221]
	v_mov_b64_e32 v[86:87], v[222:223]
	v_mov_b64_e32 v[88:89], v[224:225]
	v_mov_b64_e32 v[90:91], v[226:227]
	v_mov_b64_e32 v[92:93], v[228:229]
	v_mov_b64_e32 v[94:95], v[230:231]
	v_mov_b64_e32 v[96:97], v[232:233]
	v_mov_b64_e32 v[98:99], v[234:235]
	v_mov_b64_e32 v[100:101], v[236:237]
	v_mov_b64_e32 v[102:103], v[238:239]
	v_mov_b64_e32 v[104:105], v[240:241]
	v_mov_b64_e32 v[106:107], v[242:243]
	v_mov_b64_e32 v[108:109], v[244:245]
	s_mov_b32 s99, s98
	s_cmp_lg_u32 s98, 0
	s_cbranch_scc0 .Lmy_p14_skip
	s_waitcnt lgkmcnt(0)
	v_lshl_add_u64 v[136:137], s[72:73], 0, v[38:39]
	s_add_u32 s16, s72, s10
	v_add_co_u32_e64 v146, s[0:1], s5, v136
	s_addc_u32 s17, s73, s11
	s_nop 0
	v_addc_co_u32_e64 v147, s[0:1], 0, v137, s[0:1]
	s_add_u32 s0, s16, 0x2680000
	v_add_co_u32_e32 v144, vcc, 0x13d00000, v136
	s_addc_u32 s1, s17, 0
	s_nop 1
	v_addc_co_u32_e32 v145, vcc, 0, v137, vcc
	global_load_dwordx4 v[198:201], v32, s[16:17]
	global_load_dwordx4 v[202:205], v32, s[16:17] offset:64
	global_load_dwordx2 v[192:193], v[146:147], off
	global_load_dwordx2 v[190:191], v[146:147], off offset:512
	global_load_dwordx2 v[188:189], v[146:147], off offset:1024
	global_load_dwordx2 v[186:187], v[146:147], off offset:1536
	global_load_dwordx2 v[184:185], v[146:147], off offset:2048
	global_load_dwordx2 v[182:183], v[146:147], off offset:2560
	global_load_dwordx2 v[180:181], v[146:147], off offset:3072
	global_load_dwordx2 v[178:179], v[146:147], off offset:3584
	global_load_dwordx4 v[140:143], v32, s[16:17] offset:128
	global_load_dwordx4 v[136:139], v32, s[16:17] offset:192
	global_load_dwordx4 v[206:209], v33, s[0:1] offset:48
	global_load_dwordx4 v[210:213], v33, s[0:1] offset:16
	global_load_dwordx4 v[214:217], v33, s[0:1] offset:32
	s_add_u32 s0, s16, 0x2680040
	s_addc_u32 s1, s17, 0
	global_load_dwordx4 v[218:221], v33, s[0:1] offset:16
	global_load_dwordx4 v[222:225], v33, s[0:1] offset:48
	global_load_dwordx4 v[226:229], v33, s[0:1] offset:32
	global_load_dwordx2 v[230:231], v[144:145], off
	global_load_dwordx2 v[232:233], v[144:145], off offset:512
	global_load_dwordx2 v[234:235], v[144:145], off offset:1024
	global_load_dwordx2 v[236:237], v[144:145], off offset:1536
	global_load_dwordx2 v[238:239], v[144:145], off offset:2048
	global_load_dwordx2 v[240:241], v[144:145], off offset:2560
	global_load_dwordx2 v[242:243], v[144:145], off offset:3072
	global_load_dwordx2 v[244:245], v[144:145], off offset:3584
	s_add_u32 s0, s16, 0x2680080
	s_addc_u32 s1, s17, 0
	global_load_dwordx4 v[156:159], v33, s[0:1] offset:48
	global_load_dwordx4 v[164:167], v33, s[0:1] offset:16
	global_load_dwordx4 v[160:163], v33, s[0:1] offset:32
	s_add_u32 s0, s16, 0x26800c0
	s_addc_u32 s1, s17, 0
	global_load_dwordx4 v[152:155], v33, s[0:1] offset:16
	global_load_dwordx4 v[144:147], v33, s[0:1] offset:48
	global_load_dwordx4 v[148:151], v33, s[0:1] offset:32
	s_add_i32 s2, s2, s4
	s_add_u32 s10, s10, s12
	s_addc_u32 s11, s11, s13
	v_lshl_add_u64 v[38:39], v[38:39], 0, s[8:9]
	s_cmp_lt_i32 s2, 0x8000
	s_cselect_b32 s98, 1, 0
.Lmy_p14_skip:
	s_nop 1
	v_mov_b64_e32 v[58:59], v[120:121]
	v_mov_b64_e32 v[60:61], v[122:123]
	v_mov_b32_e32 v110, v62
	v_mov_b32_e32 v62, v64
	v_mov_b32_e32 v64, v66
	v_mov_b32_e32 v66, v68
	v_mov_b32_e32 v68, v82
	v_lshlrev_b32_e32 v112, 16, v94
	v_and_b32_e32 v113, 0xffff0000, v94
	v_mov_b32_e32 v115, v70
	v_mov_b32_e32 v114, v74
	v_mov_b32_e32 v111, v78
	v_mov_b32_e32 v78, v63
	v_mov_b32_e32 v63, v80
	v_mov_b32_e32 v80, v65
	v_mov_b32_e32 v70, v75
	v_mov_b32_e32 v74, v76
	v_mov_b32_e32 v75, v72
	v_mov_b32_e32 v72, v77
	v_pk_add_f32 v[76:77], v[110:111], v[78:79]
	v_pk_add_f32 v[62:63], v[62:63], v[80:81]
	v_pk_add_f32 v[70:71], v[114:115], v[70:71]
	v_pk_add_f32 v[72:73], v[74:75], v[72:73]
	v_pk_add_f32 v[62:63], v[76:77], v[62:63]
	v_pk_add_f32 v[70:71], v[70:71], v[72:73]
	v_mov_b32_e32 v65, v90
	v_mov_b32_e32 v90, v67
	v_mov_b32_e32 v67, v92
	v_mov_b32_e32 v92, v69
	v_mov_b32_e32 v69, v86
	v_mov_b32_e32 v86, v83
	v_mov_b32_e32 v72, v84
	v_mov_b32_e32 v73, v88
	v_mov_b32_e32 v88, v85
	v_pk_add_f32 v[62:63], v[62:63], v[70:71]
	v_pk_add_f32 v[64:65], v[64:65], v[90:91]
	v_pk_add_f32 v[66:67], v[66:67], v[92:93]
	v_pk_add_f32 v[68:69], v[68:69], v[86:87]
	v_pk_add_f32 v[70:71], v[72:73], v[88:89]
	v_pk_add_f32 v[64:65], v[64:65], v[66:67]
	v_pk_add_f32 v[66:67], v[68:69], v[70:71]
	v_mov_b32_e32 v69, v62
	v_pk_add_f32 v[64:65], v[64:65], v[66:67]
	v_lshlrev_b32_e32 v94, 16, v95
	v_mov_b32_e32 v68, v64
	v_mov_b32_e32 v62, v65
	v_pk_add_f32 v[62:63], v[68:69], v[62:63]
	v_and_b32_e32 v95, 0xffff0000, v95
	v_pk_fma_f32 v[62:63], v[62:63], s[14:15], v[40:41] op_sel_hi:[1,0,0]
	v_lshlrev_b32_e32 v70, 16, v105
	v_mul_f32_e32 v64, 0x4b800000, v63
	v_cmp_gt_f32_e32 vcc, s3, v63
	v_and_b32_e32 v71, 0xffff0000, v105
	s_nop 0
	v_cndmask_b32_e32 v63, v63, v64, vcc
	v_rsq_f32_e32 v63, v63
	s_nop 0
	v_mul_f32_e32 v64, 0x45800000, v63
	v_cndmask_b32_e32 v64, v63, v64, vcc
	v_pk_mul_f32 v[66:67], v[64:65], v[112:113] op_sel_hi:[0,1]
	v_pk_mul_f32 v[68:69], v[64:65], v[94:95] op_sel_hi:[0,1]
	v_pk_mul_f32 v[60:61], v[60:61], v[68:69]
	v_pk_mul_f32 v[58:59], v[58:59], v[66:67]
	global_store_dwordx4 v[36:37], v[58:61], off nt
	s_nop 1
	v_mov_b64_e32 v[58:59], v[124:125]
	v_mov_b64_e32 v[60:61], v[126:127]
	v_lshlrev_b32_e32 v66, 16, v96
	v_and_b32_e32 v67, 0xffff0000, v96
	v_lshlrev_b32_e32 v68, 16, v97
	v_and_b32_e32 v69, 0xffff0000, v97
	v_pk_mul_f32 v[68:69], v[64:65], v[68:69] op_sel_hi:[0,1]
	v_pk_mul_f32 v[66:67], v[64:65], v[66:67] op_sel_hi:[0,1]
	v_mul_f32_e32 v63, 0x4b800000, v62
	v_pk_mul_f32 v[58:59], v[58:59], v[66:67]
	v_pk_mul_f32 v[60:61], v[60:61], v[68:69]
	global_store_dwordx4 v[36:37], v[58:61], off offset:1024 nt
	s_nop 1
	v_mov_b64_e32 v[58:59], v[128:129]
	v_mov_b64_e32 v[60:61], v[130:131]
	v_lshlrev_b32_e32 v66, 16, v98
	v_and_b32_e32 v67, 0xffff0000, v98
	v_lshlrev_b32_e32 v68, 16, v99
	v_and_b32_e32 v69, 0xffff0000, v99
	v_pk_mul_f32 v[68:69], v[64:65], v[68:69] op_sel_hi:[0,1]
	v_pk_mul_f32 v[66:67], v[64:65], v[66:67] op_sel_hi:[0,1]
	s_nop 0
	v_pk_mul_f32 v[58:59], v[58:59], v[66:67]
	v_pk_mul_f32 v[60:61], v[60:61], v[68:69]
	global_store_dwordx4 v[36:37], v[58:61], off offset:2048 nt
	s_nop 1
	v_mov_b64_e32 v[58:59], v[132:133]
	v_mov_b64_e32 v[60:61], v[134:135]
	v_lshlrev_b32_e32 v66, 16, v100
	v_and_b32_e32 v67, 0xffff0000, v100
	v_lshlrev_b32_e32 v68, 16, v101
	v_and_b32_e32 v69, 0xffff0000, v101
	v_pk_mul_f32 v[68:69], v[64:65], v[68:69] op_sel_hi:[0,1]
	v_pk_mul_f32 v[64:65], v[64:65], v[66:67] op_sel_hi:[0,1]
	v_lshlrev_b32_e32 v66, 16, v102
	v_and_b32_e32 v67, 0xffff0000, v102
	s_nop 0
	v_pk_mul_f32 v[58:59], v[58:59], v[64:65]
	v_pk_mul_f32 v[60:61], v[60:61], v[68:69]
	global_store_dwordx4 v[36:37], v[58:61], off offset:3072 nt
	s_nop 1
	v_mov_b64_e32 v[58:59], v[120:121]
	v_mov_b64_e32 v[60:61], v[122:123]
	v_add_co_u32_e32 v64, vcc, s15, v36
	v_lshlrev_b32_e32 v68, 16, v103
	s_nop 0
	v_addc_co_u32_e32 v65, vcc, 0, v37, vcc
	v_cmp_gt_f32_e32 vcc, s3, v62
	v_and_b32_e32 v69, 0xffff0000, v103
	s_nop 0
	v_cndmask_b32_e32 v62, v62, v63, vcc
	v_rsq_f32_e32 v62, v62
	s_nop 0
	v_mul_f32_e32 v63, 0x45800000, v62
	v_cndmask_b32_e32 v62, v62, v63, vcc
	v_pk_mul_f32 v[68:69], v[62:63], v[68:69] op_sel_hi:[0,1]
	v_pk_mul_f32 v[66:67], v[62:63], v[66:67] op_sel_hi:[0,1]
	v_pk_mul_f32 v[70:71], v[62:63], v[70:71] op_sel_hi:[0,1]
	s_nop 0
	v_pk_mul_f32 v[58:59], v[58:59], v[66:67]
	v_pk_mul_f32 v[60:61], v[60:61], v[68:69]
	global_store_dwordx4 v[64:65], v[58:61], off offset:-4096 nt
	s_nop 1
	v_mov_b64_e32 v[58:59], v[124:125]
	v_mov_b64_e32 v[60:61], v[126:127]
	v_lshlrev_b32_e32 v68, 16, v104
	v_and_b32_e32 v69, 0xffff0000, v104
	v_add_co_u32_e32 v66, vcc, s18, v36
	v_pk_mul_f32 v[68:69], v[62:63], v[68:69] op_sel_hi:[0,1]
	s_nop 0
	v_addc_co_u32_e32 v67, vcc, 0, v37, vcc
	s_nop 0
	v_pk_mul_f32 v[58:59], v[58:59], v[68:69]
	v_pk_mul_f32 v[60:61], v[60:61], v[70:71]
	global_store_dwordx4 v[66:67], v[58:61], off offset:1024 nt
	s_nop 1
	v_mov_b64_e32 v[58:59], v[128:129]
	v_mov_b64_e32 v[60:61], v[130:131]
	v_lshlrev_b32_e32 v68, 16, v106
	v_and_b32_e32 v69, 0xffff0000, v106
	v_lshlrev_b32_e32 v70, 16, v107
	v_and_b32_e32 v71, 0xffff0000, v107
	v_pk_mul_f32 v[70:71], v[62:63], v[70:71] op_sel_hi:[0,1]
	v_pk_mul_f32 v[68:69], v[62:63], v[68:69] op_sel_hi:[0,1]
	s_nop 0
	v_pk_mul_f32 v[58:59], v[58:59], v[68:69]
	v_pk_mul_f32 v[60:61], v[60:61], v[70:71]
	global_store_dwordx4 v[66:67], v[58:61], off offset:2048 nt
	s_nop 1
	v_mov_b64_e32 v[58:59], v[132:133]
	v_mov_b64_e32 v[60:61], v[134:135]
	v_lshlrev_b32_e32 v68, 16, v108
	v_and_b32_e32 v69, 0xffff0000, v108
	v_lshlrev_b32_e32 v70, 16, v109
	v_and_b32_e32 v71, 0xffff0000, v109
	v_pk_mul_f32 v[70:71], v[62:63], v[70:71] op_sel_hi:[0,1]
	v_pk_mul_f32 v[62:63], v[62:63], v[68:69] op_sel_hi:[0,1]
	v_mov_b32_e32 v68, v28
	v_mov_b32_e32 v69, v20
	v_mov_b32_e32 v20, v29
	v_mov_b32_e32 v28, v30
	v_mov_b32_e32 v29, v22
	v_mov_b32_e32 v22, v31
	v_pk_add_f32 v[20:21], v[68:69], v[20:21]
	v_pk_add_f32 v[22:23], v[28:29], v[22:23]
	s_nop 0
	v_pk_mul_f32 v[58:59], v[58:59], v[62:63]
	v_pk_mul_f32 v[60:61], v[60:61], v[70:71]
	global_store_dwordx4 v[66:67], v[58:61], off offset:3072 nt
	s_nop 1
	v_mov_b64_e32 v[58:59], v[120:121]
	v_mov_b64_e32 v[60:61], v[122:123]
	v_mov_b32_e32 v62, v4
	v_mov_b32_e32 v4, v6
	v_mov_b32_e32 v6, v0
	v_mov_b32_e32 v0, v2
	v_mov_b32_e32 v63, v24
	v_mov_b32_e32 v24, v5
	v_mov_b32_e32 v5, v26
	v_mov_b32_e32 v26, v7
	v_mov_b32_e32 v7, v12
	v_mov_b32_e32 v12, v1
	v_mov_b32_e32 v1, v14
	v_mov_b32_e32 v14, v3
	v_mov_b32_e32 v2, v16
	v_mov_b32_e32 v3, v8
	v_mov_b32_e32 v8, v17
	v_mov_b32_e32 v16, v18
	v_mov_b32_e32 v17, v10
	v_mov_b32_e32 v10, v19
	v_pk_add_f32 v[24:25], v[62:63], v[24:25]
	v_pk_add_f32 v[4:5], v[4:5], v[26:27]
	v_pk_add_f32 v[6:7], v[6:7], v[12:13]
	v_pk_add_f32 v[0:1], v[0:1], v[14:15]
	v_pk_add_f32 v[2:3], v[2:3], v[8:9]
	v_pk_add_f32 v[8:9], v[16:17], v[10:11]
	v_pk_add_f32 v[4:5], v[24:25], v[4:5]
	v_pk_add_f32 v[20:21], v[20:21], v[22:23]
	v_pk_add_f32 v[0:1], v[6:7], v[0:1]
	v_pk_add_f32 v[2:3], v[2:3], v[8:9]
	v_pk_add_f32 v[4:5], v[4:5], v[20:21]
	v_pk_add_f32 v[0:1], v[0:1], v[2:3]
	v_mov_b32_e32 v7, v4
	v_mov_b32_e32 v6, v0
	v_mov_b32_e32 v4, v1
	v_pk_add_f32 v[0:1], v[6:7], v[4:5]
	v_lshlrev_b32_e32 v66, 16, v56
	v_pk_fma_f32 v[4:5], v[0:1], s[14:15], v[40:41] op_sel_hi:[1,0,0]
	v_and_b32_e32 v67, 0xffff0000, v56
	v_mul_f32_e32 v0, 0x4b800000, v5
	v_cmp_gt_f32_e32 vcc, s3, v5
	v_lshlrev_b32_e32 v56, 16, v57
	v_and_b32_e32 v57, 0xffff0000, v57
	v_cndmask_b32_e32 v0, v5, v0, vcc
	v_rsq_f32_e32 v0, v0
	v_lshlrev_b32_e32 v8, 16, v54
	v_and_b32_e32 v9, 0xffff0000, v54
	v_lshlrev_b32_e32 v10, 16, v55
	v_mul_f32_e32 v1, 0x45800000, v0
	v_cndmask_b32_e32 v6, v0, v1, vcc
	v_pk_mul_f32 v[2:3], v[6:7], v[56:57] op_sel_hi:[0,1]
	v_pk_mul_f32 v[0:1], v[6:7], v[66:67] op_sel_hi:[0,1]
	v_and_b32_e32 v11, 0xffff0000, v55
	v_pk_mul_f32 v[10:11], v[6:7], v[10:11] op_sel_hi:[0,1]
	v_pk_mul_f32 v[8:9], v[6:7], v[8:9] op_sel_hi:[0,1]
	v_mul_f32_e32 v5, 0x4b800000, v4
	s_nop 0
	v_pk_mul_f32 v[0:1], v[58:59], v[0:1]
	v_pk_mul_f32 v[2:3], v[60:61], v[2:3]
	global_store_dwordx4 v[64:65], v[0:3], off nt
	s_nop 1
	v_mov_b64_e32 v[0:1], v[124:125]
	v_mov_b64_e32 v[2:3], v[126:127]
	s_nop 0
	v_pk_mul_f32 v[0:1], v[0:1], v[8:9]
	v_pk_mul_f32 v[2:3], v[2:3], v[10:11]
	global_store_dwordx4 v[64:65], v[0:3], off offset:1024 nt
	s_nop 1
	v_mov_b64_e32 v[0:1], v[128:129]
	v_mov_b64_e32 v[2:3], v[130:131]
	v_lshlrev_b32_e32 v8, 16, v52
	v_and_b32_e32 v9, 0xffff0000, v52
	v_lshlrev_b32_e32 v10, 16, v53
	v_and_b32_e32 v11, 0xffff0000, v53
	v_pk_mul_f32 v[10:11], v[6:7], v[10:11] op_sel_hi:[0,1]
	v_pk_mul_f32 v[8:9], v[6:7], v[8:9] op_sel_hi:[0,1]
	s_nop 0
	v_pk_mul_f32 v[0:1], v[0:1], v[8:9]
	v_pk_mul_f32 v[2:3], v[2:3], v[10:11]
	global_store_dwordx4 v[64:65], v[0:3], off offset:2048 nt
	s_nop 1
	v_mov_b64_e32 v[0:1], v[132:133]
	v_mov_b64_e32 v[2:3], v[134:135]
	v_lshlrev_b32_e32 v8, 16, v50
	v_and_b32_e32 v9, 0xffff0000, v50
	v_lshlrev_b32_e32 v10, 16, v51
	v_and_b32_e32 v11, 0xffff0000, v51
	v_pk_mul_f32 v[10:11], v[6:7], v[10:11] op_sel_hi:[0,1]
	v_pk_mul_f32 v[6:7], v[6:7], v[8:9] op_sel_hi:[0,1]
	v_lshlrev_b32_e32 v8, 16, v48
	v_and_b32_e32 v9, 0xffff0000, v48
	s_nop 0
	v_pk_mul_f32 v[0:1], v[0:1], v[6:7]
	v_pk_mul_f32 v[2:3], v[2:3], v[10:11]
	global_store_dwordx4 v[64:65], v[0:3], off offset:3072 nt
	s_nop 1
	v_mov_b64_e32 v[0:1], v[120:121]
	v_mov_b64_e32 v[2:3], v[122:123]
	v_add_co_u32_e32 v6, vcc, s19, v36
	v_lshlrev_b32_e32 v10, 16, v49
	s_nop 0
	v_addc_co_u32_e32 v7, vcc, 0, v37, vcc
	v_cmp_gt_f32_e32 vcc, s3, v4
	v_and_b32_e32 v11, 0xffff0000, v49
	v_lshl_add_u64 v[36:37], v[36:37], 0, s[6:7]
	v_cndmask_b32_e32 v4, v4, v5, vcc
	v_rsq_f32_e32 v4, v4
	s_nop 0
	v_mul_f32_e32 v5, 0x45800000, v4
	v_cndmask_b32_e32 v4, v4, v5, vcc
	v_pk_mul_f32 v[10:11], v[4:5], v[10:11] op_sel_hi:[0,1]
	v_pk_mul_f32 v[8:9], v[4:5], v[8:9] op_sel_hi:[0,1]
	s_nop 0
	v_pk_mul_f32 v[0:1], v[0:1], v[8:9]
	v_pk_mul_f32 v[2:3], v[2:3], v[10:11]
	global_store_dwordx4 v[6:7], v[0:3], off nt
	s_nop 1
	v_mov_b64_e32 v[0:1], v[124:125]
	v_mov_b64_e32 v[2:3], v[126:127]
	v_lshlrev_b32_e32 v8, 16, v46
	v_and_b32_e32 v9, 0xffff0000, v46
	v_lshlrev_b32_e32 v10, 16, v47
	v_and_b32_e32 v11, 0xffff0000, v47
	v_pk_mul_f32 v[10:11], v[4:5], v[10:11] op_sel_hi:[0,1]
	v_pk_mul_f32 v[8:9], v[4:5], v[8:9] op_sel_hi:[0,1]
	s_nop 0
	v_pk_mul_f32 v[0:1], v[0:1], v[8:9]
	v_pk_mul_f32 v[2:3], v[2:3], v[10:11]
	global_store_dwordx4 v[6:7], v[0:3], off offset:1024 nt
	s_nop 1
	v_mov_b64_e32 v[0:1], v[128:129]
	v_mov_b64_e32 v[2:3], v[130:131]
	v_lshlrev_b32_e32 v8, 16, v44
	v_and_b32_e32 v9, 0xffff0000, v44
	v_lshlrev_b32_e32 v10, 16, v45
	v_and_b32_e32 v11, 0xffff0000, v45
	v_pk_mul_f32 v[10:11], v[4:5], v[10:11] op_sel_hi:[0,1]
	v_pk_mul_f32 v[8:9], v[4:5], v[8:9] op_sel_hi:[0,1]
	s_nop 0
	v_pk_mul_f32 v[0:1], v[0:1], v[8:9]
	v_pk_mul_f32 v[2:3], v[2:3], v[10:11]
	global_store_dwordx4 v[6:7], v[0:3], off offset:2048 nt
	s_nop 1
	v_mov_b64_e32 v[0:1], v[132:133]
	v_mov_b64_e32 v[2:3], v[134:135]
	v_lshlrev_b32_e32 v8, 16, v42
	v_and_b32_e32 v9, 0xffff0000, v42
	v_lshlrev_b32_e32 v10, 16, v43
	v_and_b32_e32 v11, 0xffff0000, v43
	v_pk_mul_f32 v[10:11], v[4:5], v[10:11] op_sel_hi:[0,1]
	v_pk_mul_f32 v[4:5], v[4:5], v[8:9] op_sel_hi:[0,1]
	s_nop 0
	v_pk_mul_f32 v[0:1], v[0:1], v[4:5]
	v_pk_mul_f32 v[2:3], v[2:3], v[10:11]
	global_store_dwordx4 v[6:7], v[0:3], off offset:3072 nt
	s_cmp_lg_u32 s99, 0
	s_cbranch_scc1 .LBB0_1340
